# v19 + stick-breaking diagonal masks merged on the scalar unit (16 fewer vector ops per step) + attention block-start flush waits removed
# speedup vs baseline: 1.0015x; 1.0015x over previous
.LBB0_376:
	s_cmpk_gt_i32 s78, 0x5ff
	s_mov_b64 s[0:1], -1
	s_cbranch_scc0 .LBB0_398
	s_add_i32 s0, s78, 0xfffffa00
	s_lshr_b32 s1, s0, 6
	s_and_b32 s1, s1, 12
	s_add_i32 s1, s1, s78
	s_andn2_b32 s4, 15, s1
	s_lshl_b32 s46, s4, 3
	v_readlane_b32 s66, v254, 16
	s_lshr_b32 s69, s0, 8
	s_add_i32 s79, s46, s66
	s_lshl_b32 s0, s69, 12
	s_lshl_b32 s66, s79, 5
	s_add_i32 s66, s66, s0
	s_lshl_b32 s1, s78, 3
	v_or_b32_e32 v2, s66, v165
	s_and_b32 s1, s1, 0x780
	v_lshlrev_b64 v[4:5], 12, v[2:3]
	v_lshl_add_u64 v[4:5], s[48:49], 0, v[4:5]
	s_lshl_b32 s0, s1, 1
	s_mov_b32 s1, s77
	v_lshl_add_u64 v[4:5], v[4:5], 0, s[0:1]
	v_mov_b32_e32 v173, v3
	v_lshl_add_u64 v[4:5], v[4:5], 0, v[172:173]
	global_load_dwordx4 v[132:135], v[4:5], off
	global_load_dwordx4 v[136:139], v[4:5], off offset:32
	global_load_dwordx4 v[140:143], v[4:5], off offset:64
	global_load_dwordx4 v[144:147], v[4:5], off offset:96
	global_load_dwordx4 v[148:151], v[4:5], off offset:128
	global_load_dwordx4 v[152:155], v[4:5], off offset:160
	global_load_dwordx4 v[156:159], v[4:5], off offset:192
	global_load_dwordx4 v[160:163], v[4:5], off offset:224
	s_mov_b64 s[86:87], exec
	v_readlane_b32 s66, v254, 39
	v_readlane_b32 s67, v254, 40
	s_and_b64 s[66:67], s[86:87], s[66:67]
	s_mov_b64 exec, s[66:67]
	ds_write_b32 v199, v3
	s_or_b64 exec, exec, s[86:87]
	s_lshl_b32 s1, s69, 24
	v_readlane_b32 s66, v254, 28
	v_readlane_b32 s67, v254, 29
	s_add_u32 s69, s66, s1
	s_addc_u32 s76, s67, 0
	s_add_u32 s1, s50, s1
	s_addc_u32 s67, s51, 0
	s_add_u32 s66, s1, s0
	s_addc_u32 s67, s67, 0
	s_add_u32 s86, s69, s0
	s_addc_u32 s87, s76, 0
	s_lshl_b32 s1, s46, 17
	v_lshl_add_u64 v[4:5], s[66:67], 0, v[168:169]
	v_lshlrev_b32_e32 v6, 1, v164
	v_mov_b32_e32 v7, v3
	v_lshl_add_u64 v[174:175], v[4:5], 0, v[6:7]
	v_lshl_add_u64 v[4:5], s[86:87], 0, v[168:169]
	s_or_b32 s76, s1, 0xe0000
	s_mov_b32 m0, s94
	v_lshl_add_u64 v[176:177], v[4:5], 0, v[6:7]
	v_lshl_add_u64 v[4:5], v[174:175], 0, s[76:77]
	s_lshl_b32 s4, s4, 20
	global_load_lds_dwordx4 v[4:5], off
	v_lshl_add_u64 v[4:5], v[176:177], 0, s[76:77]
	s_mov_b32 m0, s56
	s_or_b32 s76, s4, 0xc0000
	global_load_lds_dwordx4 v[4:5], off
	v_lshl_add_u64 v[4:5], v[174:175], 0, s[76:77]
	s_mov_b32 m0, s57
	v_readlane_b32 s66, v254, 0
	global_load_lds_dwordx4 v[4:5], off
	v_lshl_add_u64 v[4:5], v[176:177], 0, s[76:77]
	s_mov_b32 m0, s89
	s_or_b32 s76, s4, 0xa0000
	global_load_lds_dwordx4 v[4:5], off
	v_lshl_add_u64 v[4:5], v[174:175], 0, s[76:77]
	s_mov_b32 m0, s93
	v_readlane_b32 s67, v254, 1
	global_load_lds_dwordx4 v[4:5], off
	v_lshl_add_u64 v[4:5], v[176:177], 0, s[76:77]
	s_mov_b32 m0, s68
	s_add_i32 s76, s1, 0x80000
	global_load_lds_dwordx4 v[4:5], off
	s_waitcnt vmcnt(4)
	v_readlane_b32 s1, v254, 42
	s_waitcnt lgkmcnt(0)
	s_barrier
	v_lshl_add_u64 v[4:5], v[174:175], 0, s[76:77]
	s_mov_b32 m0, s1
	v_readlane_b32 s1, v254, 43
	global_load_lds_dwordx4 v[4:5], off
	v_lshl_add_u64 v[4:5], v[176:177], 0, s[76:77]
	s_mov_b32 m0, s1
	s_andn2_b64 vcc, exec, s[66:67]
	global_load_lds_dwordx4 v[4:5], off
	s_cbranch_vccnz .LBB0_383
	v_add_u32_e32 v1, v197, v183
	ds_read_b128 v[4:7], v1
	v_add_u32_e32 v1, v197, v184
	ds_read_b128 v[20:23], v1
	v_add_u32_e32 v1, v197, v185
	s_andn2_b64 vcc, exec, s[82:83]
	s_waitcnt lgkmcnt(0)
	v_mfma_f32_32x32x16_bf16 v[4:19], v[4:7], v[132:135], 0
	v_mfma_f32_32x32x16_bf16 v[4:19], v[20:23], v[136:139], v[4:19]
	ds_read_b128 v[20:23], v1
	v_add_u32_e32 v1, v197, v186
	ds_read_b128 v[24:27], v1
	v_add_u32_e32 v1, v197, v187
	s_waitcnt lgkmcnt(1)
	v_mfma_f32_32x32x16_bf16 v[4:19], v[20:23], v[140:143], v[4:19]
	ds_read_b128 v[20:23], v1
	v_add_u32_e32 v1, v197, v188
	s_waitcnt lgkmcnt(1)
	v_mfma_f32_32x32x16_bf16 v[4:19], v[24:27], v[144:147], v[4:19]
	ds_read_b128 v[24:27], v1
	v_add_u32_e32 v1, v197, v189
	s_waitcnt lgkmcnt(1)
	v_mfma_f32_32x32x16_bf16 v[4:19], v[20:23], v[148:151], v[4:19]
	ds_read_b128 v[20:23], v1
	v_add_u32_e32 v1, v197, v190
	s_waitcnt lgkmcnt(1)
	v_mfma_f32_32x32x16_bf16 v[4:19], v[24:27], v[152:155], v[4:19]
	ds_read_b128 v[24:27], v1
	s_waitcnt lgkmcnt(1)
	v_mfma_f32_32x32x16_bf16 v[4:19], v[20:23], v[156:159], v[4:19]
	s_waitcnt lgkmcnt(0)
	v_mfma_f32_32x32x16_bf16 v[4:19], v[24:27], v[160:163], v[4:19]
	s_nop 11
	v_exp_f32_e64 v1, -|v4|
	v_exp_f32_e64 v21, -|v5|
	v_exp_f32_e64 v23, -|v6|
	v_exp_f32_e64 v27, -|v8|
	v_exp_f32_e64 v25, -|v7|
	v_exp_f32_e64 v29, -|v9|
	v_add_f32_e32 v1, 1.0, v1
	v_exp_f32_e64 v31, -|v10|
	v_add_f32_e32 v21, 1.0, v21
	v_add_f32_e32 v23, 1.0, v23
	v_add_f32_e32 v27, 1.0, v27
	v_log_f32_e32 v1, v1
	v_log_f32_e32 v21, v21
	v_log_f32_e32 v23, v23
	v_log_f32_e32 v27, v27
	v_exp_f32_e64 v33, -|v11|
	v_add_f32_e32 v25, 1.0, v25
	v_add_f32_e32 v29, 1.0, v29
	v_max_f32_e32 v20, 0, v4
	v_log_f32_e32 v25, v25
	v_log_f32_e32 v29, v29
	v_max_f32_e32 v22, 0, v5
	v_max_f32_e32 v24, 0, v6
	v_max_f32_e32 v28, 0, v8
	v_add_f32_e32 v31, 1.0, v31
	v_add_f32_e32 v1, v20, v1
	v_log_f32_e32 v31, v31
	v_add_f32_e32 v20, v22, v21
	v_add_f32_e32 v21, v24, v23
	v_add_f32_e32 v23, v28, v27
	v_max_f32_e32 v26, 0, v7
	v_max_f32_e32 v30, 0, v9
	v_add_f32_e32 v33, 1.0, v33
	s_orn2_b64 s[98:99], s[10:11], s[82:83]
	v_cndmask_b32_e64 v27, 0, -v1, s[98:99]
	v_log_f32_e32 v33, v33
	v_add_f32_e32 v22, v26, v25
	v_add_f32_e32 v24, v30, v29
	s_orn2_b64 s[98:99], s[12:13], s[82:83]
	v_cndmask_b32_e64 v28, 0, -v20, s[98:99]
	v_add_f32_e32 v1, 0, v27
	v_max_f32_e32 v32, 0, v10
	s_orn2_b64 s[98:99], s[14:15], s[82:83]
	v_cndmask_b32_e64 v29, 0, -v21, s[98:99]
	v_add_f32_e32 v1, v28, v1
	v_exp_f32_e64 v35, -|v12|
	v_add_f32_e32 v25, v32, v31
	s_orn2_b64 s[98:99], s[16:17], s[82:83]
	v_cndmask_b32_e64 v30, 0, -v22, s[98:99]
	v_add_f32_e32 v1, v29, v1
	v_max_f32_e32 v34, 0, v11
	s_orn2_b64 s[98:99], s[18:19], s[82:83]
	v_cndmask_b32_e64 v31, 0, -v23, s[98:99]
	v_add_f32_e32 v1, v30, v1
	v_add_f32_e32 v26, v34, v33
	s_orn2_b64 s[98:99], s[20:21], s[82:83]
	v_cndmask_b32_e64 v32, 0, -v24, s[98:99]
	v_add_f32_e32 v1, v31, v1
	v_add_f32_e32 v22, v32, v1
	s_orn2_b64 s[98:99], s[24:25], s[82:83]
	v_cndmask_b32_e64 v26, 0, -v26, s[98:99]
	v_add_f32_e32 v1, 1.0, v35
	v_log_f32_e32 v1, v1
	v_exp_f32_e64 v21, -|v13|
	v_max_f32_e32 v20, 0, v12
	v_add_f32_e32 v1, v20, v1
	s_orn2_b64 s[98:99], s[26:27], s[82:83]
	v_cndmask_b32_e64 v23, 0, -v1, s[98:99]
	v_add_f32_e32 v1, 1.0, v21
	v_log_f32_e32 v1, v1
	v_max_f32_e32 v21, 0, v13
	v_add_f32_e32 v20, 0, v23
	v_add_f32_e32 v1, v21, v1
	v_exp_f32_e64 v21, -|v14|
	s_orn2_b64 s[98:99], s[28:29], s[82:83]
	v_cndmask_b32_e64 v24, 0, -v1, s[98:99]
	v_add_f32_e32 v1, v24, v20
	v_add_f32_e32 v20, 1.0, v21
	v_log_f32_e32 v20, v20
	v_exp_f32_e64 v34, -|v15|
	v_max_f32_e32 v21, 0, v14
	v_add_f32_e32 v20, v21, v20
	s_orn2_b64 s[98:99], s[30:31], s[82:83]
	v_cndmask_b32_e64 v35, 0, -v20, s[98:99]
	v_add_f32_e32 v20, 1.0, v34
	v_log_f32_e32 v20, v20
	v_max_f32_e32 v21, 0, v15
	v_exp_f32_e64 v36, -|v17|
	v_add_f32_e32 v20, v21, v20
	v_exp_f32_e64 v21, -|v16|
	s_orn2_b64 s[98:99], s[34:35], s[82:83]
	v_cndmask_b32_e64 v34, 0, -v20, s[98:99]
	v_exp_f32_e64 v38, -|v19|
	v_add_f32_e32 v20, 1.0, v21
	v_log_f32_e32 v20, v20
	v_max_f32_e32 v21, 0, v16
	v_add_f32_e32 v1, v35, v1
	v_add_f32_e32 v20, v21, v20
	s_orn2_b64 s[98:99], s[36:37], s[82:83]
	v_cndmask_b32_e64 v37, 0, -v20, s[98:99]
	v_add_f32_e32 v20, 1.0, v36
	v_log_f32_e32 v20, v20
	v_max_f32_e32 v21, 0, v17
	v_add_f32_e32 v1, v34, v1
	v_add_f32_e32 v20, v21, v20
	v_exp_f32_e64 v21, -|v18|
	s_orn2_b64 s[98:99], s[38:39], s[82:83]
	v_cndmask_b32_e64 v36, 0, -v20, s[98:99]
	v_add_f32_e32 v1, v37, v1
	v_add_f32_e32 v20, 1.0, v21
	v_log_f32_e32 v20, v20
	v_max_f32_e32 v21, 0, v18
	v_add_f32_e32 v1, v36, v1
	v_add_f32_e32 v20, v21, v20
	s_orn2_b64 s[98:99], s[40:41], s[82:83]
	v_cndmask_b32_e64 v39, 0, -v20, s[98:99]
	v_add_f32_e32 v20, 1.0, v38
	v_log_f32_e32 v20, v20
	v_max_f32_e32 v21, 0, v19
	v_add_f32_e32 v1, v39, v1
	v_add_f32_e32 v20, v21, v20
	s_orn2_b64 s[98:99], s[42:43], s[82:83]
	v_cndmask_b32_e64 v38, 0, -v20, s[98:99]
	v_add_f32_e32 v20, v38, v1
	v_mov_b32_e32 v1, v20
	v_mov_b32_e32 v21, v20
	s_nop 1
	v_permlane32_swap_b32_e32 v1, v21
	v_cndmask_b32_e64 v21, v1, v21, s[2:3]
	v_add_f32_e32 v1, 0, v21
	v_cndmask_b32_e64 v40, 0, v1, s[6:7]
	v_add_f32_e32 v42, v1, v20
	v_add_f32_e32 v1, v19, v38
	v_add_f32_e32 v19, v40, v38
	v_add_f32_e32 v18, v18, v39
	v_add_f32_e32 v18, v19, v18
	v_add_f32_e32 v19, v39, v19
	v_add_f32_e32 v17, v17, v36
	v_add_f32_e32 v17, v17, v19
	v_add_f32_e32 v19, v36, v19
	v_add_f32_e32 v16, v16, v37
	v_add_f32_e32 v16, v16, v19
	v_add_f32_e32 v19, v37, v19
	v_add_f32_e32 v15, v15, v34
	v_add_f32_e32 v15, v15, v19
	v_add_f32_e32 v19, v34, v19
	v_add_f32_e32 v14, v14, v35
	v_add_f32_e32 v14, v14, v19
	v_add_f32_e32 v19, v35, v19
	v_add_f32_e32 v13, v13, v24
	v_add_f32_e32 v13, v13, v19
	v_add_f32_e32 v19, v24, v19
	s_orn2_b64 s[98:99], s[22:23], s[82:83]
	v_cndmask_b32_e64 v24, 0, -v25, s[98:99]
	v_add_f32_e32 v22, v24, v22
	v_add_f32_e32 v22, v26, v22
	v_add_f32_e32 v12, v12, v23
	v_mov_b32_e32 v23, v22
	v_mov_b32_e32 v25, v22
	s_nop 1
	v_permlane32_swap_b32_e32 v23, v25
	v_add_f32_e32 v41, 0, v20
	v_cndmask_b32_e64 v23, v23, v25, s[2:3]
	v_add_f32_e32 v12, v12, v19
	v_add_f32_e32 v19, v41, v21
	v_add_f32_e32 v25, v42, v23
	v_add_f32_e32 v11, v11, v26
	v_cndmask_b32_e64 v25, v19, v25, s[6:7]
	v_add_f32_e32 v11, v11, v25
	v_exp_f32_e32 v19, v11
	v_mov_b32_e32 v11, v26
	v_pk_add_f32 v[10:11], v[10:11], v[24:25]
	v_add_f32_e32 v9, v9, v32
	v_add_f32_e32 v10, v10, v11
	v_add_f32_e32 v11, v24, v11
	v_add_f32_e32 v9, v9, v11
	v_add_f32_e32 v11, v32, v11
	v_add_f32_e32 v8, v8, v31
	v_add_f32_e32 v8, v8, v11
	v_add_f32_e32 v11, v31, v11
	v_add_f32_e32 v7, v7, v30
	v_add_f32_e32 v7, v7, v11
	v_add_f32_e32 v11, v30, v11
	v_add_f32_e32 v6, v6, v29
	v_add_f32_e32 v6, v6, v11
	v_add_f32_e32 v11, v29, v11
	v_add_f32_e32 v5, v5, v28
	v_add_f32_e32 v5, v5, v11
	v_add_f32_e32 v11, v28, v11
	v_add_f32_e32 v4, v4, v27
	v_add_f32_e32 v1, v40, v1
	v_add_f32_e32 v4, v4, v11
	v_exp_f32_e32 v1, v1
	v_exp_f32_e32 v18, v18
	v_exp_f32_e32 v17, v17
	v_exp_f32_e32 v16, v16
	v_exp_f32_e32 v15, v15
	v_exp_f32_e32 v14, v14
	v_exp_f32_e32 v13, v13
	v_exp_f32_e32 v12, v12
	v_exp_f32_e32 v10, v10
	v_exp_f32_e32 v9, v9
	v_exp_f32_e32 v8, v8
	v_exp_f32_e32 v7, v7
	v_exp_f32_e32 v6, v6
	v_exp_f32_e32 v5, v5
	v_exp_f32_e32 v4, v4
	s_cbranch_vccnz .LBB0_382
	s_or_b64 vcc, s[12:13], s[10:11]
	v_cndmask_b32_e32 v4, 0, v4, vcc
	s_or_b64 vcc, s[16:17], s[14:15]
	v_cndmask_b32_e32 v6, 0, v6, vcc
	s_or_b64 vcc, s[20:21], s[18:19]
	v_cndmask_b32_e32 v8, 0, v8, vcc
	s_or_b64 vcc, s[24:25], s[22:23]
	v_cndmask_b32_e32 v10, 0, v10, vcc
	s_or_b64 vcc, s[28:29], s[26:27]
	v_cndmask_b32_e32 v12, 0, v12, vcc
	s_or_b64 vcc, s[34:35], s[30:31]
	v_cndmask_b32_e32 v14, 0, v14, vcc
	s_or_b64 vcc, s[38:39], s[36:37]
	v_cndmask_b32_e32 v16, 0, v16, vcc
	s_or_b64 vcc, s[42:43], s[40:41]
	v_cndmask_b32_e64 v5, 0, v5, s[12:13]
	v_cndmask_b32_e64 v7, 0, v7, s[16:17]
	v_cndmask_b32_e64 v9, 0, v9, s[20:21]
	v_cndmask_b32_e64 v19, 0, v19, s[24:25]
	v_cndmask_b32_e64 v13, 0, v13, s[28:29]
	v_cndmask_b32_e64 v15, 0, v15, s[34:35]
	v_cndmask_b32_e64 v17, 0, v17, s[38:39]
	v_cndmask_b32_e64 v1, 0, v1, s[42:43]
	v_cndmask_b32_e32 v18, 0, v18, vcc

.LBB0_388:
	s_and_b32 s46, s69, 8
	s_xor_b32 s66, s46, 8
	s_add_i32 s67, 0, 0x10000
	s_lshl_b32 s66, s66, 2
	s_add_i32 s66, s67, s66
	v_mov_b32_e32 v1, s66
	s_waitcnt vmcnt(4)
	s_waitcnt lgkmcnt(0)
	s_barrier
	ds_read_b128 v[68:71], v1
	ds_read_b128 v[72:75], v1 offset:16
	s_mov_b64 s[90:91], -1
	s_waitcnt lgkmcnt(0)
	v_and_b32_e32 v1, v68, v69
	v_and_b32_e32 v2, v70, v71
	v_and_b32_e32 v68, v72, v73
	v_and_b32_e32 v69, v74, v75
	v_and_b32_e32 v1, v1, v2
	v_and_b32_e32 v68, v68, v69
	v_and_b32_e32 v1, v1, v68
	v_and_b32_e32 v1, 1, v1
	v_cmp_eq_u32_e32 vcc, 1, v1
	s_nop 1
	s_and_b64 vcc, exec, vcc
	s_cbranch_vccnz .LBB0_387
	s_max_i32 s66, s1, 3
	s_lshl_b32 s66, s66, 5
	s_addk_i32 s66, 0xffa0
	s_and_b32 s90, s4, 0xc000
	s_ashr_i32 s67, s66, 31
	s_lshl_b64 s[66:67], s[66:67], 12
	s_add_i32 s90, s94, s90
	v_lshl_add_u64 v[68:69], v[174:175], 0, s[66:67]
	s_mov_b32 m0, s90
	s_nop 0
	global_load_lds_dwordx4 v[68:69], off
	v_lshl_add_u64 v[68:69], v[176:177], 0, s[66:67]
	s_add_i32 m0, s90, 0x2000
	s_cmp_gt_i32 s1, s79
	global_load_lds_dwordx4 v[68:69], off
	s_cselect_b64 s[66:67], -1, 0
	s_or_b64 s[66:67], s[66:67], s[86:87]
	s_and_b64 vcc, exec, s[66:67]
	s_cbranch_vccnz .LBB0_394
	s_add_i32 s66, s4, 0xffff4000
	s_and_b32 s66, s66, 0xc000
	s_add_i32 s90, s66, 0
	v_add_u32_e32 v1, s90, v181
	v_add_u32_e32 v2, v1, v183
	ds_read_b128 v[68:71], v2
	v_add_u32_e32 v2, v1, v184
	ds_read_b128 v[84:87], v2
	v_add_u32_e32 v2, v1, v185
	ds_read_b128 v[88:91], v2
	v_add_u32_e32 v2, v1, v186
	ds_read_b128 v[228:231], v2
	v_add_u32_e32 v2, v1, v187
	ds_read_b128 v[232:235], v2
	v_add_u32_e32 v2, v1, v188
	ds_read_b128 v[236:239], v2
	v_add_u32_e32 v2, v1, v189
	ds_read_b128 v[240:243], v2
	v_add_u32_e32 v1, v1, v190
	ds_read_b128 v[244:247], v1
	s_cmp_eq_u32 s76, 0
	s_cselect_b64 s[86:87], -1, 0
	s_cmp_lg_u32 s76, 0
	s_waitcnt lgkmcnt(7)
	v_mfma_f32_32x32x16_bf16 v[68:83], v[68:71], v[132:135], 0
	s_waitcnt lgkmcnt(6)
	v_mfma_f32_32x32x16_bf16 v[68:83], v[84:87], v[136:139], v[68:83]
	s_waitcnt lgkmcnt(5)
	v_mfma_f32_32x32x16_bf16 v[68:83], v[88:91], v[140:143], v[68:83]
	s_waitcnt lgkmcnt(4)
	v_mfma_f32_32x32x16_bf16 v[68:83], v[228:231], v[144:147], v[68:83]
	s_waitcnt lgkmcnt(3)
	v_mfma_f32_32x32x16_bf16 v[68:83], v[232:235], v[148:151], v[68:83]
	s_waitcnt lgkmcnt(2)
	v_mfma_f32_32x32x16_bf16 v[68:83], v[236:239], v[152:155], v[68:83]
	s_waitcnt lgkmcnt(1)
	v_mfma_f32_32x32x16_bf16 v[68:83], v[240:243], v[156:159], v[68:83]
	s_waitcnt lgkmcnt(0)
	v_mfma_f32_32x32x16_bf16 v[68:83], v[244:247], v[160:163], v[68:83]
	v_add_u32_e32 v248, s90, v180
	v_add_u32_e32 v249, s90, v167
	v_add_u32_e32 v222, s90, v191
	v_add_u32_e32 v223, s90, v192
	v_add_u32_e32 v224, s90, v193
	v_add_u32_e32 v225, s90, v194
	v_add_u32_e32 v226, s90, v195
	v_add_u32_e32 v227, s90, v196
	ds_read_b64_tr_b16 v[228:229], v248 offset:8192
	ds_read_b64_tr_b16 v[230:231], v249 offset:9216
	ds_read_b64_tr_b16 v[232:233], v222 offset:8192
	ds_read_b64_tr_b16 v[234:235], v223 offset:8192
	ds_read_b64_tr_b16 v[236:237], v224 offset:8192
	ds_read_b64_tr_b16 v[238:239], v225 offset:8192
	ds_read_b64_tr_b16 v[240:241], v226 offset:8192
	ds_read_b64_tr_b16 v[242:243], v227 offset:8192
	v_exp_f32_e64 v1, -|v68|
	v_exp_f32_e64 v84, -|v69|
	v_exp_f32_e64 v88, -|v71|
	v_exp_f32_e64 v86, -|v70|
	v_exp_f32_e64 v90, -|v72|
	v_exp_f32_e64 v92, -|v73|
	v_add_f32_e32 v1, 1.0, v1
	v_add_f32_e32 v84, 1.0, v84
	v_add_f32_e32 v88, 1.0, v88
	v_log_f32_e32 v1, v1
	v_exp_f32_e64 v94, -|v74|
	v_add_f32_e32 v86, 1.0, v86
	v_add_f32_e32 v90, 1.0, v90
	v_log_f32_e32 v84, v84
	v_log_f32_e32 v88, v88
	v_log_f32_e32 v86, v86
	v_log_f32_e32 v90, v90
	v_max_f32_e32 v2, 0, v68
	v_add_f32_e32 v92, 1.0, v92
	v_max_f32_e32 v85, 0, v69
	v_max_f32_e32 v89, 0, v71
	v_log_f32_e32 v92, v92
	v_add_f32_e32 v1, v2, v1
	v_max_f32_e32 v87, 0, v70
	v_max_f32_e32 v91, 0, v72
	v_add_f32_e32 v94, 1.0, v94
	v_add_f32_e32 v2, v85, v84
	v_add_f32_e32 v85, v89, v88
	v_log_f32_e32 v94, v94
	v_add_f32_e32 v84, v87, v86
	v_add_f32_e32 v86, v91, v90
	s_orn2_b64 s[98:99], s[10:11], s[86:87]
	v_cndmask_b32_e64 v98, 0, -v1, s[98:99]
	v_max_f32_e32 v93, 0, v73
	s_orn2_b64 s[98:99], s[12:13], s[86:87]
	v_cndmask_b32_e64 v90, 0, -v2, s[98:99]
	v_add_f32_e32 v1, 0, v98
	v_exp_f32_e64 v96, -|v75|
	v_add_f32_e32 v87, v93, v92
	s_orn2_b64 s[98:99], s[14:15], s[86:87]
	v_cndmask_b32_e64 v91, 0, -v84, s[98:99]
	v_add_f32_e32 v1, v90, v1
	v_max_f32_e32 v95, 0, v74
	s_orn2_b64 s[98:99], s[16:17], s[86:87]
	v_cndmask_b32_e64 v92, 0, -v85, s[98:99]
	v_add_f32_e32 v1, v91, v1
	v_add_f32_e32 v88, v95, v94
	s_orn2_b64 s[98:99], s[18:19], s[86:87]
	v_cndmask_b32_e64 v93, 0, -v86, s[98:99]
	v_add_f32_e32 v1, v92, v1
	s_orn2_b64 s[98:99], s[20:21], s[86:87]
	v_cndmask_b32_e64 v87, 0, -v87, s[98:99]
	v_add_f32_e32 v1, v93, v1
	v_add_f32_e32 v96, 1.0, v96
	v_add_f32_e32 v86, v87, v1
	v_exp_f32_e64 v1, -|v76|
	v_log_f32_e32 v96, v96
	v_max_f32_e32 v97, 0, v75
	v_add_f32_e32 v1, 1.0, v1
	v_add_f32_e32 v2, v97, v96
	v_log_f32_e32 v1, v1
	s_orn2_b64 s[98:99], s[24:25], s[86:87]
	v_cndmask_b32_e64 v94, 0, -v2, s[98:99]
	v_exp_f32_e64 v84, -|v77|
	v_max_f32_e32 v2, 0, v76
	v_add_f32_e32 v1, v2, v1
	s_orn2_b64 s[98:99], s[26:27], s[86:87]
	v_cndmask_b32_e64 v89, 0, -v1, s[98:99]
	v_add_f32_e32 v1, 1.0, v84
	v_log_f32_e32 v1, v1
	v_max_f32_e32 v84, 0, v77
	v_add_f32_e32 v2, 0, v89
	v_add_f32_e32 v1, v84, v1
	v_exp_f32_e64 v84, -|v78|
	s_orn2_b64 s[98:99], s[28:29], s[86:87]
	v_cndmask_b32_e64 v96, 0, -v1, s[98:99]
	v_add_f32_e32 v1, v96, v2
	v_add_f32_e32 v2, 1.0, v84
	v_log_f32_e32 v2, v2
	v_exp_f32_e64 v85, -|v79|
	v_max_f32_e32 v84, 0, v78
	v_add_f32_e32 v2, v84, v2
	s_orn2_b64 s[98:99], s[30:31], s[86:87]
	v_cndmask_b32_e64 v97, 0, -v2, s[98:99]
	v_add_f32_e32 v2, 1.0, v85
	v_log_f32_e32 v2, v2
	v_max_f32_e32 v84, 0, v79
	v_add_f32_e32 v1, v97, v1
	v_add_f32_e32 v2, v84, v2
	v_exp_f32_e64 v84, -|v80|
	s_orn2_b64 s[98:99], s[34:35], s[86:87]
	v_cndmask_b32_e64 v99, 0, -v2, s[98:99]
	v_exp_f32_e64 v85, -|v81|
	v_add_f32_e32 v2, 1.0, v84
	v_log_f32_e32 v2, v2
	v_max_f32_e32 v84, 0, v80
	v_add_f32_e32 v1, v99, v1
	v_add_f32_e32 v2, v84, v2
	s_orn2_b64 s[98:99], s[36:37], s[86:87]
	v_cndmask_b32_e64 v100, 0, -v2, s[98:99]
	v_add_f32_e32 v2, 1.0, v85
	v_log_f32_e32 v2, v2
	v_max_f32_e32 v84, 0, v81
	v_add_f32_e32 v1, v100, v1
	v_add_f32_e32 v2, v84, v2
	v_exp_f32_e64 v84, -|v82|
	s_orn2_b64 s[98:99], s[38:39], s[86:87]
	v_cndmask_b32_e64 v101, 0, -v2, s[98:99]
	v_exp_f32_e64 v85, -|v83|
	v_add_f32_e32 v2, 1.0, v84
	v_log_f32_e32 v2, v2
	v_max_f32_e32 v84, 0, v82
	v_add_f32_e32 v1, v101, v1
	v_add_f32_e32 v2, v84, v2
	s_orn2_b64 s[98:99], s[40:41], s[86:87]
	v_cndmask_b32_e64 v102, 0, -v2, s[98:99]
	v_add_f32_e32 v2, 1.0, v85
	v_log_f32_e32 v2, v2
	v_max_f32_e32 v84, 0, v83
	v_add_f32_e32 v1, v102, v1
	v_add_f32_e32 v2, v84, v2
	s_orn2_b64 s[98:99], s[42:43], s[86:87]
	v_cndmask_b32_e64 v2, 0, -v2, s[98:99]
	v_add_f32_e32 v84, v2, v1
	v_mov_b32_e32 v1, v84
	v_mov_b32_e32 v85, v84
	s_nop 1
	v_permlane32_swap_b32_e32 v1, v85
	v_cndmask_b32_e64 v85, v1, v85, s[2:3]
	v_add_f32_e32 v1, v173, v85
	v_cndmask_b32_e64 v103, v173, v1, s[6:7]
	v_add_f32_e32 v105, v1, v84
	v_add_f32_e32 v1, v83, v2
	v_add_f32_e32 v83, v103, v2
	v_add_f32_e32 v2, v82, v102
	v_add_f32_e32 v82, v102, v83
	v_add_f32_e32 v81, v81, v101
	v_add_f32_e32 v81, v81, v82
	v_add_f32_e32 v82, v101, v82
	v_add_f32_e32 v80, v80, v100
	v_add_f32_e32 v80, v80, v82
	v_add_f32_e32 v82, v100, v82
	v_add_f32_e32 v79, v79, v99
	v_add_f32_e32 v79, v79, v82
	v_add_f32_e32 v82, v99, v82
	v_add_f32_e32 v78, v78, v97
	v_add_f32_e32 v78, v78, v82
	v_add_f32_e32 v82, v97, v82
	v_add_f32_e32 v77, v77, v96
	v_add_f32_e32 v77, v77, v82
	v_add_f32_e32 v82, v96, v82
	v_add_f32_e32 v76, v76, v89
	s_orn2_b64 s[98:99], s[22:23], s[86:87]
	v_cndmask_b32_e64 v88, 0, -v88, s[98:99]
	v_add_f32_e32 v76, v76, v82
	v_add_f32_e32 v82, v88, v86
	v_add_f32_e32 v82, v94, v82
	v_mov_b32_e32 v86, v82
	v_mov_b32_e32 v89, v82
	s_nop 1
	v_permlane32_swap_b32_e32 v86, v89
	v_add_f32_e32 v104, v173, v84
	v_cndmask_b32_e64 v86, v86, v89, s[2:3]
	v_add_f32_e32 v2, v83, v2
	v_add_f32_e32 v83, v104, v85
	v_add_f32_e32 v89, v105, v86
	v_add_f32_e32 v75, v75, v94
	v_cndmask_b32_e64 v89, v83, v89, s[6:7]
	v_add_f32_e32 v75, v75, v89
	v_exp_f32_e32 v83, v75
	v_mov_b32_e32 v75, v94
	v_pk_add_f32 v[74:75], v[74:75], v[88:89]
	v_add_f32_e32 v73, v73, v87
	v_add_f32_e32 v74, v74, v75
	v_add_f32_e32 v75, v88, v75
	v_add_f32_e32 v73, v73, v75
	v_add_f32_e32 v75, v87, v75
	v_add_f32_e32 v72, v72, v93
	v_add_f32_e32 v72, v72, v75
	v_add_f32_e32 v75, v93, v75
	v_add_f32_e32 v71, v71, v92
	v_add_f32_e32 v71, v71, v75
	v_add_f32_e32 v75, v92, v75
	v_add_f32_e32 v70, v70, v91
	v_add_f32_e32 v70, v70, v75
	v_add_f32_e32 v75, v91, v75
	v_add_f32_e32 v69, v69, v90
	v_add_f32_e32 v69, v69, v75
	v_add_f32_e32 v75, v90, v75
	v_add_f32_e32 v68, v68, v98
	v_add_f32_e32 v1, v103, v1
	v_add_f32_e32 v68, v68, v75
	v_exp_f32_e32 v1, v1
	v_exp_f32_e32 v2, v2
	v_exp_f32_e32 v81, v81
	v_exp_f32_e32 v80, v80
	v_exp_f32_e32 v79, v79
	v_exp_f32_e32 v78, v78
	v_exp_f32_e32 v77, v77
	v_exp_f32_e32 v76, v76
	v_exp_f32_e32 v74, v74
	v_exp_f32_e32 v73, v73
	v_exp_f32_e32 v72, v72
	v_exp_f32_e32 v71, v71
	v_exp_f32_e32 v70, v70
	v_exp_f32_e32 v69, v69
	v_exp_f32_e32 v68, v68
	s_cmp_lg_u32 s76, 0
	s_cbranch_scc1 .LBB0_392
	s_or_b64 vcc, s[12:13], s[10:11]
	v_cndmask_b32_e32 v68, 0, v68, vcc
	s_or_b64 vcc, s[16:17], s[14:15]
	v_cndmask_b32_e32 v70, 0, v70, vcc
	s_or_b64 vcc, s[20:21], s[18:19]
	v_cndmask_b32_e32 v72, 0, v72, vcc
	s_or_b64 vcc, s[24:25], s[22:23]
	v_cndmask_b32_e32 v74, 0, v74, vcc
	s_or_b64 vcc, s[28:29], s[26:27]
	v_cndmask_b32_e32 v76, 0, v76, vcc
	s_or_b64 vcc, s[34:35], s[30:31]
	v_cndmask_b32_e32 v78, 0, v78, vcc
	s_or_b64 vcc, s[38:39], s[36:37]
	v_cndmask_b32_e32 v80, 0, v80, vcc
	s_or_b64 vcc, s[42:43], s[40:41]
	v_cndmask_b32_e64 v69, 0, v69, s[12:13]
	v_cndmask_b32_e64 v71, 0, v71, s[16:17]
	v_cndmask_b32_e64 v73, 0, v73, s[20:21]
	v_cndmask_b32_e64 v83, 0, v83, s[24:25]
	v_cndmask_b32_e64 v77, 0, v77, s[28:29]
	v_cndmask_b32_e64 v79, 0, v79, s[34:35]
	v_cndmask_b32_e64 v81, 0, v81, s[38:39]
	v_cndmask_b32_e64 v1, 0, v1, s[42:43]
	v_cndmask_b32_e32 v2, 0, v2, vcc
